# v49 + FF1 K-loop: load phases at priority 1, MFMA phases at priority 0 (mid-phase flips removed)
# baseline (speedup 1.0000x reference)
.LBB0_211:
	s_add_i32 s73, s58, 2
	s_add_u32 s74, s56, 0x80
	s_addc_u32 s59, s57, 0
	s_add_i32 s78, 0, 0x10000
	s_cmp_eq_u32 s63, s58
	s_cselect_b32 s59, s51, s59
	s_cselect_b32 s58, s55, s74
	v_add_u32_e32 v0, s78, v146
	s_cselect_b32 s75, s45, s72
	s_cselect_b32 s74, s44, s67
	s_add_i32 s80, 0, 0x14000
	ds_read_b128 v[148:151], v0
	ds_read_b128 v[152:155], v0 offset:1024
	ds_read_b128 v[156:159], v0 offset:2048
	ds_read_b128 v[160:163], v0 offset:3072
	v_add_u32_e32 v0, s80, v146
	ds_read_b128 v[164:167], v0
	ds_read_b128 v[168:171], v0 offset:1024
	ds_read_b128 v[172:175], v0 offset:2048
	ds_read_b128 v[176:179], v0 offset:3072
	s_mov_b32 m0, s31
	v_lshl_add_u64 v[142:143], s[56:57], 0, v[136:137]
	global_load_lds_dwordx4 v[142:143], off
	v_lshl_add_u64 v[142:143], s[56:57], 0, v[132:133]
	s_mov_b32 m0, s53
	s_nop 0
	global_load_lds_dwordx4 v[142:143], off
	v_lshl_add_u64 v[142:143], s[56:57], 0, v[138:139]
	s_add_i32 m0, s27, 0xc000
	s_nop 0
	global_load_lds_dwordx4 v[142:143], off
	v_lshl_add_u64 v[142:143], s[56:57], 0, v[140:141]
	s_add_i32 m0, s27, 0xe000
	s_nop 0
	global_load_lds_dwordx4 v[142:143], off
	ds_read_b128 v[180:183], v147
	ds_read_b128 v[184:187], v147 offset:1024
	ds_read_b128 v[200:203], v147 offset:2048
	ds_read_b128 v[204:207], v147 offset:3072
	ds_read_b128 v[208:211], v147 offset:4096
	ds_read_b128 v[212:215], v147 offset:5120
	ds_read_b128 v[216:219], v147 offset:6144
	ds_read_b128 v[220:223], v147 offset:7168
	s_waitcnt vmcnt(8)
	s_waitcnt lgkmcnt(0)
	s_barrier
	s_setprio 0
	s_waitcnt lgkmcnt(0)
	v_mfma_f32_16x16x32_bf16 v[122:125], v[148:151], v[180:183], v[122:125]
	v_mfma_f32_16x16x32_bf16 v[126:129], v[156:159], v[180:183], v[126:129]
	v_mfma_f32_16x16x32_bf16 v[110:113], v[148:151], v[200:203], v[110:113]
	v_mfma_f32_16x16x32_bf16 v[106:109], v[156:159], v[200:203], v[106:109]
	v_mfma_f32_16x16x32_bf16 v[94:97], v[148:151], v[208:211], v[94:97]
	v_mfma_f32_16x16x32_bf16 v[90:93], v[156:159], v[208:211], v[90:93]
	v_mfma_f32_16x16x32_bf16 v[78:81], v[148:151], v[216:219], v[78:81]
	v_mfma_f32_16x16x32_bf16 v[74:77], v[156:159], v[216:219], v[74:77]
	v_mfma_f32_16x16x32_bf16 v[122:125], v[152:155], v[184:187], v[122:125]
	v_mfma_f32_16x16x32_bf16 v[126:129], v[160:163], v[184:187], v[126:129]
	v_mfma_f32_16x16x32_bf16 v[110:113], v[152:155], v[204:207], v[110:113]
	v_mfma_f32_16x16x32_bf16 v[106:109], v[160:163], v[204:207], v[106:109]
	v_mfma_f32_16x16x32_bf16 v[94:97], v[152:155], v[212:215], v[94:97]
	v_mfma_f32_16x16x32_bf16 v[90:93], v[160:163], v[212:215], v[90:93]
	v_mfma_f32_16x16x32_bf16 v[78:81], v[152:155], v[220:223], v[78:81]
	v_mfma_f32_16x16x32_bf16 v[74:77], v[160:163], v[220:223], v[74:77]
	v_mfma_f32_16x16x32_bf16 v[118:121], v[164:167], v[180:183], v[118:121]
	v_mfma_f32_16x16x32_bf16 v[114:117], v[172:175], v[180:183], v[114:117]
	v_mfma_f32_16x16x32_bf16 v[102:105], v[164:167], v[200:203], v[102:105]
	v_mfma_f32_16x16x32_bf16 v[98:101], v[172:175], v[200:203], v[98:101]
	v_mfma_f32_16x16x32_bf16 v[86:89], v[164:167], v[208:211], v[86:89]
	v_mfma_f32_16x16x32_bf16 v[82:85], v[172:175], v[208:211], v[82:85]
	v_mfma_f32_16x16x32_bf16 v[70:73], v[164:167], v[216:219], v[70:73]
	v_mfma_f32_16x16x32_bf16 v[66:69], v[172:175], v[216:219], v[66:69]
	v_mfma_f32_16x16x32_bf16 v[118:121], v[168:171], v[184:187], v[118:121]
	v_mfma_f32_16x16x32_bf16 v[114:117], v[176:179], v[184:187], v[114:117]
	v_mfma_f32_16x16x32_bf16 v[102:105], v[168:171], v[204:207], v[102:105]
	v_mfma_f32_16x16x32_bf16 v[98:101], v[176:179], v[204:207], v[98:101]
	v_mfma_f32_16x16x32_bf16 v[86:89], v[168:171], v[212:215], v[86:89]
	v_mfma_f32_16x16x32_bf16 v[82:85], v[176:179], v[212:215], v[82:85]
	v_mfma_f32_16x16x32_bf16 v[70:73], v[168:171], v[220:223], v[70:73]
	v_mfma_f32_16x16x32_bf16 v[66:69], v[176:179], v[220:223], v[66:69]
	s_setprio 1
	s_barrier
	s_add_i32 s78, s78, s5
	v_lshl_add_u64 v[142:143], s[74:75], 0, v[134:135]
	s_mov_b32 m0, s78
	ds_read_b128 v[180:183], v147 offset:16384
	ds_read_b128 v[184:187], v147 offset:17408
	ds_read_b128 v[200:203], v147 offset:18432
	ds_read_b128 v[204:207], v147 offset:19456
	ds_read_b128 v[208:211], v147 offset:20480
	ds_read_b128 v[212:215], v147 offset:21504
	ds_read_b128 v[216:219], v147 offset:22528
	ds_read_b128 v[220:223], v147 offset:23552
	global_load_lds_dwordx4 v[142:143], off
	s_add_i32 m0, s78, 0x2000
	v_lshl_add_u64 v[188:189], s[74:75], 0, v[130:131]
	s_add_u32 s74, s74, s6
	s_addc_u32 s75, s75, s7
	s_add_i32 s78, s80, s5
	global_load_lds_dwordx4 v[188:189], off
	v_lshl_add_u64 v[224:225], s[74:75], 0, v[134:135]
	s_mov_b32 m0, s78
	v_lshl_add_u64 v[226:227], s[74:75], 0, v[130:131]
	global_load_lds_dwordx4 v[224:225], off
	s_add_i32 m0, s78, 0x2000
	v_lshl_add_u64 v[228:229], s[58:59], 0, v[136:137]
	global_load_lds_dwordx4 v[226:227], off
	v_lshl_add_u64 v[230:231], s[58:59], 0, v[132:133]
	s_waitcnt vmcnt(6)
	s_waitcnt lgkmcnt(0)
	s_barrier
	s_setprio 0
	s_waitcnt lgkmcnt(0)
	v_mfma_f32_16x16x32_bf16 v[62:65], v[148:151], v[180:183], v[62:65]
	v_mfma_f32_16x16x32_bf16 v[58:61], v[156:159], v[180:183], v[58:61]
	v_mfma_f32_16x16x32_bf16 v[46:49], v[148:151], v[200:203], v[46:49]
	v_mfma_f32_16x16x32_bf16 v[42:45], v[156:159], v[200:203], v[42:45]
	v_mfma_f32_16x16x32_bf16 v[30:33], v[148:151], v[208:211], v[30:33]
	v_mfma_f32_16x16x32_bf16 v[26:29], v[156:159], v[208:211], v[26:29]
	v_mfma_f32_16x16x32_bf16 v[14:17], v[148:151], v[216:219], v[14:17]
	v_mfma_f32_16x16x32_bf16 v[10:13], v[156:159], v[216:219], v[10:13]
	v_mfma_f32_16x16x32_bf16 v[62:65], v[152:155], v[184:187], v[62:65]
	v_mfma_f32_16x16x32_bf16 v[58:61], v[160:163], v[184:187], v[58:61]
	v_mfma_f32_16x16x32_bf16 v[46:49], v[152:155], v[204:207], v[46:49]
	v_mfma_f32_16x16x32_bf16 v[42:45], v[160:163], v[204:207], v[42:45]
	v_mfma_f32_16x16x32_bf16 v[30:33], v[152:155], v[212:215], v[30:33]
	v_mfma_f32_16x16x32_bf16 v[26:29], v[160:163], v[212:215], v[26:29]
	v_mfma_f32_16x16x32_bf16 v[14:17], v[152:155], v[220:223], v[14:17]
	v_mfma_f32_16x16x32_bf16 v[10:13], v[160:163], v[220:223], v[10:13]
	v_mfma_f32_16x16x32_bf16 v[54:57], v[164:167], v[180:183], v[54:57]
	v_mfma_f32_16x16x32_bf16 v[50:53], v[172:175], v[180:183], v[50:53]
	v_mfma_f32_16x16x32_bf16 v[38:41], v[164:167], v[200:203], v[38:41]
	v_mfma_f32_16x16x32_bf16 v[34:37], v[172:175], v[200:203], v[34:37]
	v_mfma_f32_16x16x32_bf16 v[22:25], v[164:167], v[208:211], v[22:25]
	v_mfma_f32_16x16x32_bf16 v[18:21], v[172:175], v[208:211], v[18:21]
	v_mfma_f32_16x16x32_bf16 v[6:9], v[164:167], v[216:219], v[6:9]
	v_mfma_f32_16x16x32_bf16 v[2:5], v[172:175], v[216:219], v[2:5]
	v_mfma_f32_16x16x32_bf16 v[54:57], v[168:171], v[184:187], v[54:57]
	v_mfma_f32_16x16x32_bf16 v[50:53], v[176:179], v[184:187], v[50:53]
	v_mfma_f32_16x16x32_bf16 v[38:41], v[168:171], v[204:207], v[38:41]
	v_mfma_f32_16x16x32_bf16 v[34:37], v[176:179], v[204:207], v[34:37]
	v_mfma_f32_16x16x32_bf16 v[22:25], v[168:171], v[212:215], v[22:25]
	v_mfma_f32_16x16x32_bf16 v[18:21], v[176:179], v[212:215], v[18:21]
	v_mfma_f32_16x16x32_bf16 v[6:9], v[168:171], v[220:223], v[6:9]
	v_mfma_f32_16x16x32_bf16 v[2:5], v[176:179], v[220:223], v[2:5]
	s_setprio 1
	s_barrier
	s_add_i32 s74, 0, 0x18000
	v_add_u32_e32 v0, s74, v146
	s_add_i32 s75, 0, 0x1c000
	ds_read_b128 v[148:151], v0
	ds_read_b128 v[152:155], v0 offset:1024
	ds_read_b128 v[156:159], v0 offset:2048
	ds_read_b128 v[160:163], v0 offset:3072
	v_add_u32_e32 v0, s75, v146
	ds_read_b128 v[164:167], v0
	ds_read_b128 v[168:171], v0 offset:1024
	ds_read_b128 v[172:175], v0 offset:2048
	ds_read_b128 v[176:179], v0 offset:3072
	s_add_u32 s58, s58, s2
	s_addc_u32 s59, s59, s3
	s_mov_b32 m0, s27
	v_lshl_add_u64 v[232:233], s[58:59], 0, v[136:137]
	s_nop 0
	global_load_lds_dwordx4 v[228:229], off
	s_mov_b32 m0, s28
	s_nop 0
	global_load_lds_dwordx4 v[230:231], off
	s_mov_b32 m0, s29
	s_nop 0
	global_load_lds_dwordx4 v[232:233], off
	v_lshl_add_u64 v[232:233], s[58:59], 0, v[132:133]
	s_mov_b32 m0, s30
	s_nop 0
	global_load_lds_dwordx4 v[232:233], off
	ds_read_b128 v[180:183], v147 offset:32768
	ds_read_b128 v[184:187], v147 offset:33792
	ds_read_b128 v[200:203], v147 offset:34816
	ds_read_b128 v[204:207], v147 offset:35840
	ds_read_b128 v[208:211], v147 offset:36864
	ds_read_b128 v[212:215], v147 offset:37888
	ds_read_b128 v[216:219], v147 offset:38912
	ds_read_b128 v[220:223], v147 offset:39936
	s_waitcnt vmcnt(8)
	s_waitcnt lgkmcnt(0)
	s_barrier
	s_setprio 0
	s_waitcnt lgkmcnt(0)
	v_mfma_f32_16x16x32_bf16 v[122:125], v[148:151], v[180:183], v[122:125]
	v_mfma_f32_16x16x32_bf16 v[126:129], v[156:159], v[180:183], v[126:129]
	v_mfma_f32_16x16x32_bf16 v[110:113], v[148:151], v[200:203], v[110:113]
	v_mfma_f32_16x16x32_bf16 v[106:109], v[156:159], v[200:203], v[106:109]
	v_mfma_f32_16x16x32_bf16 v[94:97], v[148:151], v[208:211], v[94:97]
	v_mfma_f32_16x16x32_bf16 v[90:93], v[156:159], v[208:211], v[90:93]
	v_mfma_f32_16x16x32_bf16 v[78:81], v[148:151], v[216:219], v[78:81]
	v_mfma_f32_16x16x32_bf16 v[74:77], v[156:159], v[216:219], v[74:77]
	v_mfma_f32_16x16x32_bf16 v[122:125], v[152:155], v[184:187], v[122:125]
	v_mfma_f32_16x16x32_bf16 v[126:129], v[160:163], v[184:187], v[126:129]
	v_mfma_f32_16x16x32_bf16 v[110:113], v[152:155], v[204:207], v[110:113]
	v_mfma_f32_16x16x32_bf16 v[106:109], v[160:163], v[204:207], v[106:109]
	v_mfma_f32_16x16x32_bf16 v[94:97], v[152:155], v[212:215], v[94:97]
	v_mfma_f32_16x16x32_bf16 v[90:93], v[160:163], v[212:215], v[90:93]
	v_mfma_f32_16x16x32_bf16 v[78:81], v[152:155], v[220:223], v[78:81]
	v_mfma_f32_16x16x32_bf16 v[74:77], v[160:163], v[220:223], v[74:77]
	v_mfma_f32_16x16x32_bf16 v[118:121], v[164:167], v[180:183], v[118:121]
	v_mfma_f32_16x16x32_bf16 v[114:117], v[172:175], v[180:183], v[114:117]
	v_mfma_f32_16x16x32_bf16 v[102:105], v[164:167], v[200:203], v[102:105]
	v_mfma_f32_16x16x32_bf16 v[98:101], v[172:175], v[200:203], v[98:101]
	v_mfma_f32_16x16x32_bf16 v[86:89], v[164:167], v[208:211], v[86:89]
	v_mfma_f32_16x16x32_bf16 v[82:85], v[172:175], v[208:211], v[82:85]
	v_mfma_f32_16x16x32_bf16 v[70:73], v[164:167], v[216:219], v[70:73]
	v_mfma_f32_16x16x32_bf16 v[66:69], v[172:175], v[216:219], v[66:69]
	v_mfma_f32_16x16x32_bf16 v[118:121], v[168:171], v[184:187], v[118:121]
	v_mfma_f32_16x16x32_bf16 v[114:117], v[176:179], v[184:187], v[114:117]
	v_mfma_f32_16x16x32_bf16 v[102:105], v[168:171], v[204:207], v[102:105]
	v_mfma_f32_16x16x32_bf16 v[98:101], v[176:179], v[204:207], v[98:101]
	v_mfma_f32_16x16x32_bf16 v[86:89], v[168:171], v[212:215], v[86:89]
	v_mfma_f32_16x16x32_bf16 v[82:85], v[176:179], v[212:215], v[82:85]
	v_mfma_f32_16x16x32_bf16 v[70:73], v[168:171], v[220:223], v[70:73]
	v_mfma_f32_16x16x32_bf16 v[66:69], v[176:179], v[220:223], v[66:69]
	s_setprio 1
	s_barrier
	s_add_i32 s58, s74, s5
	v_lshl_add_u64 v[142:143], v[142:143], 0, s[24:25]
	s_mov_b32 m0, s58
	ds_read_b128 v[180:183], v147 offset:49152
	ds_read_b128 v[184:187], v147 offset:50176
	ds_read_b128 v[200:203], v147 offset:51200
	ds_read_b128 v[204:207], v147 offset:52224
	ds_read_b128 v[208:211], v147 offset:53248
	ds_read_b128 v[212:215], v147 offset:54272
	ds_read_b128 v[216:219], v147 offset:55296
	ds_read_b128 v[220:223], v147 offset:56320
	global_load_lds_dwordx4 v[142:143], off
	v_lshl_add_u64 v[142:143], v[188:189], 0, s[24:25]
	s_add_i32 m0, s58, 0x2000
	s_add_i32 s58, s75, s5
	global_load_lds_dwordx4 v[142:143], off
	v_lshl_add_u64 v[142:143], v[224:225], 0, s[24:25]
	s_mov_b32 m0, s58
	s_nop 0
	global_load_lds_dwordx4 v[142:143], off
	v_lshl_add_u64 v[142:143], v[226:227], 0, s[24:25]
	s_add_i32 m0, s58, 0x2000
	s_nop 0
	global_load_lds_dwordx4 v[142:143], off
	s_waitcnt vmcnt(6)
	s_waitcnt lgkmcnt(0)
	s_barrier
	s_setprio 0
	s_waitcnt lgkmcnt(0)
	v_mfma_f32_16x16x32_bf16 v[62:65], v[148:151], v[180:183], v[62:65]
	v_mfma_f32_16x16x32_bf16 v[58:61], v[156:159], v[180:183], v[58:61]
	v_mfma_f32_16x16x32_bf16 v[46:49], v[148:151], v[200:203], v[46:49]
	v_mfma_f32_16x16x32_bf16 v[42:45], v[156:159], v[200:203], v[42:45]
	v_mfma_f32_16x16x32_bf16 v[30:33], v[148:151], v[208:211], v[30:33]
	v_mfma_f32_16x16x32_bf16 v[26:29], v[156:159], v[208:211], v[26:29]
	v_mfma_f32_16x16x32_bf16 v[14:17], v[148:151], v[216:219], v[14:17]
	v_mfma_f32_16x16x32_bf16 v[10:13], v[156:159], v[216:219], v[10:13]
	v_mfma_f32_16x16x32_bf16 v[62:65], v[152:155], v[184:187], v[62:65]
	v_mfma_f32_16x16x32_bf16 v[58:61], v[160:163], v[184:187], v[58:61]
	v_mfma_f32_16x16x32_bf16 v[46:49], v[152:155], v[204:207], v[46:49]
	v_mfma_f32_16x16x32_bf16 v[42:45], v[160:163], v[204:207], v[42:45]
	v_mfma_f32_16x16x32_bf16 v[30:33], v[152:155], v[212:215], v[30:33]
	v_mfma_f32_16x16x32_bf16 v[26:29], v[160:163], v[212:215], v[26:29]
	v_mfma_f32_16x16x32_bf16 v[14:17], v[152:155], v[220:223], v[14:17]
	v_mfma_f32_16x16x32_bf16 v[10:13], v[160:163], v[220:223], v[10:13]
	v_mfma_f32_16x16x32_bf16 v[54:57], v[164:167], v[180:183], v[54:57]
	v_mfma_f32_16x16x32_bf16 v[50:53], v[172:175], v[180:183], v[50:53]
	v_mfma_f32_16x16x32_bf16 v[38:41], v[164:167], v[200:203], v[38:41]
	v_mfma_f32_16x16x32_bf16 v[34:37], v[172:175], v[200:203], v[34:37]
	v_mfma_f32_16x16x32_bf16 v[22:25], v[164:167], v[208:211], v[22:25]
	v_mfma_f32_16x16x32_bf16 v[18:21], v[172:175], v[208:211], v[18:21]
	v_mfma_f32_16x16x32_bf16 v[6:9], v[164:167], v[216:219], v[6:9]
	v_mfma_f32_16x16x32_bf16 v[2:5], v[172:175], v[216:219], v[2:5]
	v_mfma_f32_16x16x32_bf16 v[54:57], v[168:171], v[184:187], v[54:57]
	v_mfma_f32_16x16x32_bf16 v[50:53], v[176:179], v[184:187], v[50:53]
	v_mfma_f32_16x16x32_bf16 v[38:41], v[168:171], v[204:207], v[38:41]
	v_mfma_f32_16x16x32_bf16 v[34:37], v[176:179], v[204:207], v[34:37]
	v_mfma_f32_16x16x32_bf16 v[22:25], v[168:171], v[212:215], v[22:25]
	v_mfma_f32_16x16x32_bf16 v[18:21], v[176:179], v[212:215], v[18:21]
	v_mfma_f32_16x16x32_bf16 v[6:9], v[168:171], v[220:223], v[6:9]
	v_mfma_f32_16x16x32_bf16 v[2:5], v[176:179], v[220:223], v[2:5]
	s_setprio 1
	s_barrier
	s_add_u32 s56, s56, 0x100
	s_addc_u32 s57, s57, 0
	s_add_u32 s67, s67, 0x100
	s_addc_u32 s72, s72, 0
	s_cmp_ge_i32 s73, s60
	s_mov_b32 s58, s73
	s_cbranch_scc0 .LBB0_211
	v_readlane_b32 s74, v236, 30
	v_readlane_b32 s75, v236, 31
	v_readlane_b32 s73, v236, 32
	s_mov_b32 s78, s76
